# P10 cross-attention work queue: sample (HBM-bound) and prompt (MFMA-bound) units alternate in the queue instead of one class after the other
# baseline (speedup 1.0000x reference)
.LBB0_1217:
	s_or_b64 exec, exec, s[0:1]
	s_bitcmp0_b32 s17, 0
	s_cselect_b32 s16, 0x200, 0
	s_waitcnt vmcnt(6)
	v_mov_b32_e32 v67, v0
	s_lshr_b32 s17, s17, 1
	s_add_i32 s16, s16, s17
	s_mov_b64 s[0:1], -1
	v_ashrrev_i32_e32 v12, 4, v67
	v_add_u32_e32 v2, 0x200, v67
	v_add_u32_e32 v3, 0x400, v67
	v_add_u32_e32 v4, 0x600, v67
	v_add_u32_e32 v5, 0x800, v67
	v_add_u32_e32 v7, 0xa00, v67
	v_readfirstlane_b32 s11, v67
	s_cmpk_gt_i32 s16, 0x1ff
	v_and_b32_e32 v14, 15, v67
	v_ashrrev_i32_e32 v13, 31, v12
	v_lshlrev_b32_e32 v15, 8, v12
	v_lshlrev_b32_e32 v17, 2, v12
	v_bfe_u32 v16, v12, 2, 2
	v_ashrrev_i32_e32 v10, 4, v2
	v_ashrrev_i32_e32 v8, 4, v3
	v_ashrrev_i32_e32 v6, 4, v4
	v_ashrrev_i32_e32 v4, 4, v5
	v_ashrrev_i32_e32 v2, 4, v7
	s_waitcnt vmcnt(5)
	v_add_u32_e32 v19, 0xc00, v67
	v_add_u32_e32 v18, 0xe00, v67
	s_cbranch_scc0 .LBB0_1219
	s_add_i32 s0, s16, 0xfffffe00
	s_lshr_b32 s2, s0, 2
	s_and_b32 s10, s16, 3
	s_lshl_b64 s[0:1], s[2:3], 17
	s_lshl_b32 s4, s10, 7
	v_lshlrev_b64 v[20:21], 9, v[12:13]
	s_or_b32 s0, s0, s4
	v_ashrrev_i32_e32 v11, 31, v10
	v_lshlrev_b32_e32 v66, 3, v14
	v_lshl_add_u64 v[20:21], v[20:21], 0, s[0:1]
	v_lshlrev_b64 v[36:37], 9, v[10:11]
	v_or_b32_e32 v20, v20, v66
	v_lshl_add_u64 v[36:37], v[36:37], 0, s[0:1]
	v_lshlrev_b64 v[28:29], 2, v[20:21]
	v_or_b32_e32 v36, v36, v66
	s_waitcnt vmcnt(4)
	v_lshl_add_u64 v[24:25], s[86:87], 0, v[28:29]
	v_lshlrev_b64 v[44:45], 2, v[36:37]
	global_load_dwordx4 v[20:23], v[24:25], off offset:16
	s_nop 0
	global_load_dwordx4 v[24:27], v[24:25], off
	v_lshl_add_u64 v[32:33], s[88:89], 0, v[28:29]
	v_lshl_add_u64 v[40:41], s[86:87], 0, v[44:45]
	v_lshl_add_u64 v[48:49], s[88:89], 0, v[44:45]
	global_load_dwordx4 v[28:31], v[32:33], off offset:16
	s_nop 0
	global_load_dwordx4 v[32:35], v[32:33], off
	s_nop 0
	global_load_dwordx4 v[36:39], v[40:41], off
	s_nop 0
	global_load_dwordx4 v[40:43], v[40:41], off offset:16
	s_nop 0
	global_load_dwordx4 v[44:47], v[48:49], off
	s_nop 0
	global_load_dwordx4 v[48:51], v[48:49], off offset:16
	v_ashrrev_i32_e32 v9, 31, v8
	v_lshlrev_b64 v[52:53], 9, v[8:9]
	v_lshl_add_u64 v[52:53], v[52:53], 0, s[0:1]
	v_or_b32_e32 v52, v52, v66
	v_lshlrev_b64 v[60:61], 2, v[52:53]
	v_lshl_add_u64 v[56:57], s[86:87], 0, v[60:61]
	global_load_dwordx4 v[52:55], v[56:57], off
	s_nop 0
	global_load_dwordx4 v[56:59], v[56:57], off offset:16
	v_lshl_add_u64 v[68:69], s[88:89], 0, v[60:61]
	global_load_dwordx4 v[60:63], v[68:69], off offset:16
	s_nop 0
	global_load_dwordx4 v[68:71], v[68:69], off
	v_ashrrev_i32_e32 v7, 31, v6
	v_lshlrev_b64 v[64:65], 9, v[6:7]
	v_ashrrev_i32_e32 v5, 31, v4
	v_lshl_add_u64 v[64:65], v[64:65], 0, s[0:1]
	s_waitcnt vmcnt(14)
	v_lshlrev_b64 v[72:73], 9, v[4:5]
	v_or_b32_e32 v64, v64, v66
	v_lshlrev_b32_e32 v11, 2, v10
	v_lshl_add_u64 v[72:73], v[72:73], 0, s[0:1]
	v_lshlrev_b64 v[64:65], 2, v[64:65]
	v_bfe_u32 v74, v10, 2, 2
	v_and_b32_e32 v11, 12, v11
	v_or_b32_e32 v72, v72, v66
	v_lshl_add_u64 v[76:77], s[86:87], 0, v[64:65]
	v_bitop3_b32 v5, v11, v14, v74 bitop3:0x36
	s_waitcnt vmcnt(13)
	v_lshlrev_b64 v[96:97], 2, v[72:73]
	global_load_dwordx4 v[72:75], v[76:77], off offset:16
	s_nop 0
	global_load_dwordx4 v[76:79], v[76:77], off
	v_and_b32_e32 v3, 12, v17
	v_bitop3_b32 v3, v3, v14, v16 bitop3:0x36
	v_lshlrev_b32_e32 v9, 8, v10
	v_lshl_or_b32 v3, v3, 4, v15
	v_add_u32_e32 v7, 0, v3
	v_add_u32_e32 v3, s80, v3
	v_lshl_or_b32 v5, v5, 4, v9
	v_lshl_add_u64 v[64:65], s[88:89], 0, v[64:65]
	v_lshl_add_u64 v[92:93], s[86:87], 0, v[96:97]
	v_add_u32_e32 v9, 0, v5
	global_load_dwordx4 v[80:83], v[64:65], off offset:16
	global_load_dwordx4 v[84:87], v[64:65], off
	global_load_dwordx4 v[88:91], v[92:93], off offset:16
	s_nop 0
	global_load_dwordx4 v[92:95], v[92:93], off
	v_ashrrev_i32_e32 v64, 4, v19
	v_ashrrev_i32_e32 v65, 31, v64
	v_ashrrev_i32_e32 v104, 4, v18
	v_ashrrev_i32_e32 v105, 31, v104
	s_lshl_b32 s2, s2, 3
	s_add_i32 s4, s2, 0x8000
	s_mov_b32 s5, s3
	s_waitcnt vmcnt(16)
	v_cvt_pk_bf16_f32 v24, v24, v25
	v_cvt_pk_bf16_f32 v25, v26, v27
	v_cvt_pk_bf16_f32 v26, v20, v21
	v_cvt_pk_bf16_f32 v27, v22, v23
	s_waitcnt vmcnt(14)
	v_cvt_pk_bf16_f32 v20, v32, v33
	v_cvt_pk_bf16_f32 v21, v34, v35
	v_cvt_pk_bf16_f32 v22, v28, v29
	v_cvt_pk_bf16_f32 v23, v30, v31
	s_waitcnt vmcnt(13)
	v_cvt_pk_bf16_f32 v28, v36, v37
	v_cvt_pk_bf16_f32 v29, v38, v39
	s_waitcnt vmcnt(12)
	v_cvt_pk_bf16_f32 v30, v40, v41
	v_cvt_pk_bf16_f32 v31, v42, v43
	s_waitcnt vmcnt(11)
	v_cvt_pk_bf16_f32 v32, v44, v45
	v_cvt_pk_bf16_f32 v33, v46, v47
	s_waitcnt vmcnt(10)
	v_cvt_pk_bf16_f32 v34, v48, v49
	ds_write_b128 v7, v[24:27]
	ds_write_b128 v3, v[20:23]
	ds_write_b128 v9, v[28:31]
	v_cvt_pk_bf16_f32 v35, v50, v51
	v_add_u32_e32 v3, s80, v5
	ds_write_b128 v3, v[32:35]
	v_lshl_add_u64 v[22:23], s[88:89], 0, v[96:97]
	v_ashrrev_i32_e32 v3, 31, v2
	global_load_dwordx4 v[24:27], v[22:23], off offset:16
	global_load_dwordx4 v[28:31], v[22:23], off
	v_lshlrev_b64 v[22:23], 9, v[2:3]
	v_lshl_add_u64 v[22:23], v[22:23], 0, s[0:1]
	v_or_b32_e32 v22, v22, v66
	v_lshlrev_b64 v[40:41], 2, v[22:23]
	v_lshlrev_b32_e32 v5, 2, v8
	v_lshlrev_b64 v[48:49], 9, v[64:65]
	v_lshl_add_u64 v[22:23], s[86:87], 0, v[40:41]
	v_and_b32_e32 v5, 12, v5
	v_bfe_u32 v7, v8, 2, 2
	v_lshl_add_u64 v[48:49], v[48:49], 0, s[0:1]
	global_load_dwordx4 v[32:35], v[22:23], off offset:16
	global_load_dwordx4 v[36:39], v[22:23], off
	v_lshlrev_b32_e32 v3, 8, v8
	v_or_b32_e32 v48, v48, v66
	v_bitop3_b32 v5, v5, v14, v7 bitop3:0x36
	s_waitcnt vmcnt(12)
	v_cvt_pk_bf16_f32 v22, v56, v57
	v_lshl_add_u64 v[44:45], s[88:89], 0, v[40:41]
	v_lshlrev_b64 v[56:57], 2, v[48:49]
	v_lshl_or_b32 v3, v5, 4, v3
	v_cvt_pk_bf16_f32 v20, v52, v53
	v_cvt_pk_bf16_f32 v21, v54, v55
	v_cvt_pk_bf16_f32 v23, v58, v59
	global_load_dwordx4 v[40:43], v[44:45], off offset:16
	s_nop 0
	global_load_dwordx4 v[44:47], v[44:45], off
	v_lshl_add_u64 v[52:53], s[86:87], 0, v[56:57]
	v_add_u32_e32 v5, 0, v3
	global_load_dwordx4 v[48:51], v[52:53], off offset:16
	s_nop 0
	global_load_dwordx4 v[52:55], v[52:53], off
	ds_write_b128 v5, v[20:23]
	v_lshl_add_u64 v[22:23], s[88:89], 0, v[56:57]
	s_waitcnt vmcnt(14)
	v_cvt_pk_bf16_f32 v20, v68, v69
	v_cvt_pk_bf16_f32 v21, v70, v71
	global_load_dwordx4 v[56:59], v[22:23], off offset:16
	global_load_dwordx4 v[68:71], v[22:23], off
	v_lshlrev_b64 v[22:23], 9, v[104:105]
	v_lshl_add_u64 v[22:23], v[22:23], 0, s[0:1]
	v_or_b32_e32 v22, v22, v66
	v_lshlrev_b64 v[106:107], 2, v[22:23]
	v_lshl_add_u64 v[22:23], s[86:87], 0, v[106:107]
	global_load_dwordx4 v[96:99], v[22:23], off offset:16
	global_load_dwordx4 v[100:103], v[22:23], off
	v_cvt_pk_bf16_f32 v22, v60, v61
	v_cvt_pk_bf16_f32 v23, v62, v63
	v_add_u32_e32 v3, s80, v3
	ds_write_b128 v3, v[20:23]
	s_waitcnt vmcnt(17)
	v_cvt_pk_bf16_f32 v22, v72, v73
	v_lshl_add_u64 v[72:73], s[88:89], 0, v[106:107]
	v_cvt_pk_bf16_f32 v23, v74, v75
	global_load_dwordx4 v[60:63], v[72:73], off offset:16
	s_nop 0
	global_load_dwordx4 v[72:75], v[72:73], off
	v_lshlrev_b32_e32 v5, 2, v6
	v_and_b32_e32 v5, 12, v5
	v_bfe_u32 v7, v6, 2, 2
	v_lshlrev_b32_e32 v3, 8, v6
	v_bitop3_b32 v5, v5, v14, v7 bitop3:0x36
	v_lshl_or_b32 v3, v5, 4, v3
	s_waitcnt vmcnt(18)
	v_cvt_pk_bf16_f32 v20, v76, v77
	v_cvt_pk_bf16_f32 v21, v78, v79
	v_add_u32_e32 v5, 0, v3
	ds_write_b128 v5, v[20:23]
	v_lshlrev_b32_e32 v5, 2, v4
	s_waitcnt vmcnt(16)
	v_cvt_pk_bf16_f32 v20, v84, v85
	v_cvt_pk_bf16_f32 v21, v86, v87
	v_cvt_pk_bf16_f32 v22, v80, v81
	v_cvt_pk_bf16_f32 v23, v82, v83
	v_add_u32_e32 v3, s80, v3
	v_and_b32_e32 v5, 12, v5
	v_bfe_u32 v7, v4, 2, 2
	ds_write_b128 v3, v[20:23]
	v_lshlrev_b32_e32 v3, 8, v4
	v_bitop3_b32 v5, v5, v14, v7 bitop3:0x36
	v_lshl_or_b32 v3, v5, 4, v3
	s_waitcnt vmcnt(14)
	v_cvt_pk_bf16_f32 v20, v92, v93
	v_cvt_pk_bf16_f32 v21, v94, v95
	v_cvt_pk_bf16_f32 v22, v88, v89
	v_cvt_pk_bf16_f32 v23, v90, v91
	v_add_u32_e32 v5, 0, v3
	ds_write_b128 v5, v[20:23]
	v_lshlrev_b32_e32 v5, 2, v2
	v_add_u32_e32 v3, s80, v3
	v_and_b32_e32 v5, 12, v5
	v_bfe_u32 v7, v2, 2, 2
	v_bitop3_b32 v5, v5, v14, v7 bitop3:0x36
	v_bfe_u32 v7, v64, 2, 2
	s_waitcnt vmcnt(13)
	v_cvt_pk_bf16_f32 v22, v24, v25
	s_waitcnt vmcnt(12)
	v_cvt_pk_bf16_f32 v20, v28, v29
	v_cvt_pk_bf16_f32 v21, v30, v31
	v_cvt_pk_bf16_f32 v23, v26, v27
	ds_write_b128 v3, v[20:23]
	v_lshlrev_b32_e32 v3, 8, v2
	v_lshl_or_b32 v3, v5, 4, v3
	v_add_u32_e32 v5, 0, v3
	v_add_u32_e32 v3, s80, v3
	s_mov_b64 s[0:1], 0
	s_waitcnt vmcnt(11)
	v_cvt_pk_bf16_f32 v22, v32, v33
	s_waitcnt vmcnt(10)
	v_cvt_pk_bf16_f32 v20, v36, v37
	v_cvt_pk_bf16_f32 v21, v38, v39
	v_cvt_pk_bf16_f32 v23, v34, v35
	ds_write_b128 v5, v[20:23]
	v_lshlrev_b32_e32 v5, 2, v64
	v_and_b32_e32 v5, 12, v5
	v_bitop3_b32 v5, v5, v14, v7 bitop3:0x36
	v_bfe_u32 v7, v104, 2, 2
	s_waitcnt vmcnt(9)
	v_cvt_pk_bf16_f32 v22, v40, v41
	s_waitcnt vmcnt(8)
	v_cvt_pk_bf16_f32 v20, v44, v45
	v_cvt_pk_bf16_f32 v21, v46, v47
	v_cvt_pk_bf16_f32 v23, v42, v43
	ds_write_b128 v3, v[20:23]
	v_lshlrev_b32_e32 v3, 8, v64
	v_lshl_or_b32 v3, v5, 4, v3
	s_waitcnt vmcnt(6)
	v_cvt_pk_bf16_f32 v20, v52, v53
	v_cvt_pk_bf16_f32 v21, v54, v55
	v_cvt_pk_bf16_f32 v22, v48, v49
	v_cvt_pk_bf16_f32 v23, v50, v51
	v_add_u32_e32 v5, 0, v3
	ds_write_b128 v5, v[20:23]
	v_lshlrev_b32_e32 v5, 2, v104
	s_waitcnt vmcnt(4)
	v_cvt_pk_bf16_f32 v20, v68, v69
	v_cvt_pk_bf16_f32 v21, v70, v71
	v_cvt_pk_bf16_f32 v22, v56, v57
	v_cvt_pk_bf16_f32 v23, v58, v59
	v_add_u32_e32 v3, s80, v3
	v_and_b32_e32 v5, 12, v5
	ds_write_b128 v3, v[20:23]
	v_lshlrev_b32_e32 v3, 8, v104
	v_bitop3_b32 v5, v5, v14, v7 bitop3:0x36
	v_lshl_or_b32 v3, v5, 4, v3
	s_waitcnt vmcnt(2)
	v_cvt_pk_bf16_f32 v20, v100, v101
	v_cvt_pk_bf16_f32 v21, v102, v103
	v_cvt_pk_bf16_f32 v22, v96, v97
	v_cvt_pk_bf16_f32 v23, v98, v99
	v_add_u32_e32 v5, 0, v3
	ds_write_b128 v5, v[20:23]
	s_waitcnt vmcnt(0)
	v_cvt_pk_bf16_f32 v20, v72, v73
	v_cvt_pk_bf16_f32 v21, v74, v75
	v_cvt_pk_bf16_f32 v22, v60, v61
	v_cvt_pk_bf16_f32 v23, v62, v63
	v_add_u32_e32 v3, s80, v3
	ds_write_b128 v3, v[20:23]
